# v12 + SGU causal-mix MFMA loop with batched LDS reads + QKV epilogue re-emitted with all loads hoisted
# speedup vs baseline: 1.0144x; 1.0099x over previous
; #define LAS __attribute__((address_space(3)))
; __device__ __forceinline__ void sgu_phase(const PL& P, LAS unsigned char* lds, int vcu, int G, int tid, int wave, int lane) {
;     ...
;             for (int ks = 0; ks < nks; ++ks) {
;                 const bf16x8 af = *(const LAS bf16x8*)(Wt + (16 * wave + fr) * ST + 32 * ks + 8 * fq);
; #pragma unroll
;                 for (int n = 0; n < 8; ++n) { const bf16x8 bfv = *(const LAS bf16x8*)(Vt + (16 * n + fr) * ST + 32 * ks + 8 * fq);
;                     acc[n] = __builtin_amdgcn_mfma_f32_16x16x32_bf16(bfv, af, acc[n], 0, 0, 0); }
;             }
.LBB0_273:
	ds_read_b128 v[92:95], v70
	ds_read_b128 v[120:123], v71
	ds_read_b128 v[124:127], v71 offset:4352
	ds_read_b128 v[128:131], v71 offset:8704
	ds_read_b128 v[132:135], v89
	ds_read_b128 v[136:139], v71 offset:17408
	ds_read_b128 v[140:143], v71 offset:21760
	ds_read_b128 v[144:147], v71 offset:26112
	ds_read_b128 v[148:151], v90
	s_add_i32 s0, s0, -1
	v_add_u32_e32 v70, 64, v70
	v_add_u32_e32 v89, 64, v89
	v_add_u32_e32 v71, 64, v71
	v_add_u32_e32 v90, 64, v90
	s_cmp_eq_u32 s0, 0
	s_waitcnt lgkmcnt(7)
	v_mfma_f32_16x16x32_bf16 v[28:31], v[120:123], v[92:95], v[28:31]
	s_waitcnt lgkmcnt(6)
	v_mfma_f32_16x16x32_bf16 v[24:27], v[124:127], v[92:95], v[24:27]
	s_waitcnt lgkmcnt(5)
	v_mfma_f32_16x16x32_bf16 v[20:23], v[128:131], v[92:95], v[20:23]
	s_waitcnt lgkmcnt(4)
	v_mfma_f32_16x16x32_bf16 v[16:19], v[132:135], v[92:95], v[16:19]
	s_waitcnt lgkmcnt(3)
	v_mfma_f32_16x16x32_bf16 v[12:15], v[136:139], v[92:95], v[12:15]
	s_waitcnt lgkmcnt(2)
	v_mfma_f32_16x16x32_bf16 v[8:11], v[140:143], v[92:95], v[8:11]
	s_waitcnt lgkmcnt(1)
	v_mfma_f32_16x16x32_bf16 v[4:7], v[144:147], v[92:95], v[4:7]
	s_waitcnt lgkmcnt(0)
	v_mfma_f32_16x16x32_bf16 v[0:3], v[148:151], v[92:95], v[0:3]
	s_cbranch_scc0 .LBB0_273
	s_branch .LBB0_270

;     static __device__ __forceinline__ void run(const f32x4 (&acc)[2][2][4][2], const Unit& u, int wr, int wc, int fr, int fq, bf16_t* Q, bf16_t* K, bf16_t* V, const float* qg, const float* kg, float qscale, const float* ssqA, const float* bvec) {
;         const int b = (u.pm * BM) >> 13; const int sect = u.pn >> 2; const int row0 = u.pm * BM + wr * 64 + fr; const int colb = (u.pn & 3) * 256 + 64 * wc + 8 * fq;
;         bf16_t* base = sect == 0 ? Q : (sect == 1 ? K : V);
;         const float* gp = (sect == 0 ? qg : kg) + 8 * fq; const float sc = sect == 0 ? qscale : 1.0f;
;         const float* bp = bvec + ((unsigned)b * 3072u + (unsigned)(u.pn * BM + wc * 32 + 8 * fq));
; #pragma unroll
;         for (int ai = 0; ai < 2; ++ai)
; #pragma unroll
;             for (int m = 0; m < 4; ++m) {
;                 const int row = row0 + ai * HALF + m * 16; const float r = row_scale(ssqA, nullptr, row);
;                 f32x4 v[2][2]; float ss = 0.f;
; #pragma unroll
;                 for (int bj = 0; bj < 2; ++bj)
; #pragma unroll
;                     for (int n = 0; n < 2; ++n) { const f32x4 x = acc[ai][bj][m][n] * r + *(const f32x4*)(bp + bj * HALF + 4 * n); v[bj][n] = x; ss += (x[0] * x[0] + x[1] * x[1]) + (x[2] * x[2] + x[3] * x[3]); }
;                 ss = xadd<16>(ss); ss = xadd<32>(ss);
;                 const float rs = sect < 2 ? __builtin_amdgcn_rsqf(ss * (1.0f / 64.0f) + 1e-6f) * sc : 1.0f;
;                 bf16_t* rowp = base + ((unsigned)row * 1024u + (unsigned)colb);
;     __device__ __forceinline__ unsigned u(int i) const { return (unsigned)__builtin_amdgcn_readfirstlane((int)d[i]); }
;     template <class T> __device__ __forceinline__ T* p(int i) const { const unsigned long long lo = u(i), hi = u(i + 1); return (T*)(__attribute__((address_space(1))) T*)((hi << 32) | lo); }
;     __device__ __forceinline__ void operator()(const f32x4 (&acc)[2][2][4][2], const Unit& un, int wr, int wc, int fr, int fq) const {
;         const int kind = (int)u(0);
;         { const int t_ = opaque_tid(), w_ = __builtin_amdgcn_readfirstlane(t_ >> 6), l_ = t_ & 63; wr = w_ >> 2; wc = w_ & 3; fr = l_ & 15; fq = l_ >> 4; }
;         if ((EPIMASK & 1) && kind == 0) EpiSwiglu::run(acc, un, wr, wc, fr, fq, p<bf16_t>(4), (int)u(1), p<const float>(14), p<const float>(16), p<const float>(18));
.LBB0_444:
	s_and_b64 vcc, exec, s[8:9]
	s_cbranch_vccz .LBB0_479
	s_cmp_eq_u32 s66, 2
	s_mov_b64 s[2:3], -1
	s_cbranch_scc0 .LBB0_479
	v_mov_b32_e32 v128, 0x20810
	ds_read_b128 v[128:131], v128
	v_mov_b32_e32 v132, 0x20820
	ds_read_b128 v[132:135], v132
	v_mov_b32_e32 v136, 0x20830
	ds_read_b128 v[136:139], v136
	v_mov_b32_e32 v140, 0x20848
	ds_read_b64 v[140:141], v140
	v_mov_b32_e32 v142, 0x20808
	ds_read_b32 v142, v142
	s_ashr_i32 s2, s62, 2
	s_waitcnt lgkmcnt(0)
	v_readfirstlane_b32 s8, v128
	v_readfirstlane_b32 s9, v129
	v_readfirstlane_b32 s10, v130
	v_readfirstlane_b32 s11, v131
	v_readfirstlane_b32 s28, v132
	v_readfirstlane_b32 s29, v133
	s_cmp_eq_u32 s2, 1
	s_cselect_b32 s8, s10, s8
	s_cselect_b32 s9, s11, s9
	s_cmp_eq_u32 s2, 2
	s_cselect_b32 s8, s28, s8
	s_cselect_b32 s9, s29, s9
	v_readfirstlane_b32 s10, v134
	v_readfirstlane_b32 s11, v135
	v_readfirstlane_b32 s28, v136
	v_readfirstlane_b32 s29, v137
	s_cmp_eq_u32 s2, 0
	s_cselect_b32 s10, s10, s28
	s_cselect_b32 s11, s11, s29
	v_readfirstlane_b32 s34, v142
	s_cselect_b32 s34, s34, 1.0
	v_readfirstlane_b32 s28, v138
	v_readfirstlane_b32 s29, v139
	v_readfirstlane_b32 s30, v140
	v_readfirstlane_b32 s31, v141
	s_lshl_b32 s3, s63, 8
	s_lshl_b32 s2, s65, 6
	s_add_i32 s3, s3, s2
	v_or_b32_e32 v143, s3, v230
	v_mov_b32_e32 v145, 0
	v_lshlrev_b32_e32 v144, 2, v143
	v_lshl_add_u64 v[144:145], s[28:29], 0, v[144:145]
	global_load_dword v172, v[144:145], off
	global_load_dword v173, v[144:145], off offset:64
	global_load_dword v174, v[144:145], off offset:128
	global_load_dword v175, v[144:145], off offset:192
	global_load_dword v180, v[144:145], off offset:512
	global_load_dword v181, v[144:145], off offset:576
	global_load_dword v182, v[144:145], off offset:640
	global_load_dword v183, v[144:145], off offset:704
	s_lshr_b32 s2, s63, 5
	s_mul_i32 s2, s2, 0xc00
	s_lshl_b32 s3, s62, 8
	s_add_i32 s2, s2, s3
	s_lshl_b32 s3, s64, 5
	s_add_i32 s2, s2, s3
	v_lshl_add_u32 v146, v229, 3, s2
	v_lshlrev_b32_e32 v146, 2, v146
	v_mov_b32_e32 v147, 0
	v_lshl_add_u64 v[146:147], s[30:31], 0, v[146:147]
	global_load_dwordx4 v[184:187], v[146:147], off
	global_load_dwordx4 v[188:191], v[146:147], off offset:16
	global_load_dwordx4 v[192:195], v[146:147], off offset:512
	global_load_dwordx4 v[196:199], v[146:147], off offset:528
	s_ashr_i32 s2, s62, 2
	s_cmp_lt_u32 s2, 2
	s_cbranch_scc0 .Lqkv_nogain
	v_lshlrev_b32_e32 v148, 5, v229
	v_mov_b32_e32 v149, 0
	v_lshl_add_u64 v[148:149], s[10:11], 0, v[148:149]
	global_load_dwordx4 v[200:203], v[148:149], off
	global_load_dwordx4 v[204:207], v[148:149], off offset:16
	global_load_dwordx4 v[208:211], v[148:149], off offset:128
	global_load_dwordx4 v[212:215], v[148:149], off offset:144
	s_branch .Lqkv_gain_done
.Lqkv_nogain:
	v_mov_b32_e32 v200, 1.0
	v_mov_b32_e32 v201, 1.0
	v_mov_b32_e32 v202, 1.0
	v_mov_b32_e32 v203, 1.0
	v_mov_b32_e32 v204, 1.0
	v_mov_b32_e32 v205, 1.0
	v_mov_b32_e32 v206, 1.0
	v_mov_b32_e32 v207, 1.0
	v_mov_b32_e32 v208, 1.0
	v_mov_b32_e32 v209, 1.0
	v_mov_b32_e32 v210, 1.0
	v_mov_b32_e32 v211, 1.0
	v_mov_b32_e32 v212, 1.0
	v_mov_b32_e32 v213, 1.0
	v_mov_b32_e32 v214, 1.0
	v_mov_b32_e32 v215, 1.0
.Lqkv_gain_done:
	s_and_b32 s3, s62, 3
	s_lshl_b32 s3, s3, 8
	s_lshl_b32 s2, s64, 6
	s_add_i32 s3, s3, s2
	v_lshl_add_u32 v150, v229, 3, s3
	v_lshl_add_u32 v150, v143, 10, v150
	v_lshlrev_b32_e32 v150, 1, v150
	v_mov_b32_e32 v151, 0
	v_lshl_add_u64 v[150:151], s[8:9], 0, v[150:151]
	s_ashr_i32 s2, s62, 2
	s_cmp_lt_u32 s2, 2
	s_cselect_b64 vcc, -1, 0
	s_waitcnt vmcnt(0)
	v_fmamk_f32 v152, v172, 0x3a800000, v222
	v_rsq_f32_e32 v152, v152
	s_nop 0
	v_pk_fma_f32 v[128:129], v[124:125], v[152:153], v[184:185] op_sel_hi:[1,0,1]
	v_pk_fma_f32 v[130:131], v[126:127], v[152:153], v[186:187] op_sel_hi:[1,0,1]
	v_pk_fma_f32 v[132:133], v[120:121], v[152:153], v[188:189] op_sel_hi:[1,0,1]
	v_pk_fma_f32 v[134:135], v[122:123], v[152:153], v[190:191] op_sel_hi:[1,0,1]
	v_pk_fma_f32 v[136:137], v[116:117], v[152:153], v[192:193] op_sel_hi:[1,0,1]
	v_pk_fma_f32 v[138:139], v[118:119], v[152:153], v[194:195] op_sel_hi:[1,0,1]
	v_pk_fma_f32 v[140:141], v[112:113], v[152:153], v[196:197] op_sel_hi:[1,0,1]
	v_pk_fma_f32 v[142:143], v[114:115], v[152:153], v[198:199] op_sel_hi:[1,0,1]
	v_mul_f32_e32 v154, v129, v129
	v_mul_f32_e32 v155, v131, v131
	v_fmac_f32_e32 v154, v128, v128
	v_fmac_f32_e32 v155, v130, v130
	v_add_f32_e32 v154, v154, v155
	v_add_f32_e32 v153, 0, v154
	v_mul_f32_e32 v154, v133, v133
	v_mul_f32_e32 v155, v135, v135
	v_fmac_f32_e32 v154, v132, v132
	v_fmac_f32_e32 v155, v134, v134
	v_add_f32_e32 v154, v154, v155
	v_add_f32_e32 v153, v153, v154
	v_mul_f32_e32 v154, v137, v137
	v_mul_f32_e32 v155, v139, v139
	v_fmac_f32_e32 v154, v136, v136
	v_fmac_f32_e32 v155, v138, v138
	v_add_f32_e32 v154, v154, v155
	v_add_f32_e32 v153, v153, v154
	v_mul_f32_e32 v154, v141, v141
	v_mul_f32_e32 v155, v143, v143
	v_fmac_f32_e32 v154, v140, v140
	v_fmac_f32_e32 v155, v142, v142
	v_add_f32_e32 v154, v154, v155
	v_add_f32_e32 v153, v153, v154
	ds_swizzle_b32 v154, v153 offset:swizzle(SWAP,16)
	s_waitcnt lgkmcnt(0)
; __device__ __forceinline__ unsigned cvt_pk_bf16(float lo, float hi) { unsigned r; asm volatile("v_cvt_pk_bf16_f32 %0, %1, %2" : "=v"(r) : "v"(lo), "v"(hi)); return r; }
;     static __device__ __forceinline__ void run(const f32x4 (&acc)[2][2][4][2], const Unit& u, int wr, int wc, int fr, int fq, bf16_t* Q, bf16_t* K, bf16_t* V, const float* qg, const float* kg, float qscale, const float* ssqA, const float* bvec) {
;     ...
;                 const int row = row0 + ai * HALF + m * 16; const float r = row_scale(ssqA, nullptr, row);
;                 f32x4 v[2][2]; float ss = 0.f;
; #pragma unroll
;                 for (int bj = 0; bj < 2; ++bj)
; #pragma unroll
;                     for (int n = 0; n < 2; ++n) { const f32x4 x = acc[ai][bj][m][n] * r + *(const f32x4*)(bp + bj * HALF + 4 * n); v[bj][n] = x; ss += (x[0] * x[0] + x[1] * x[1]) + (x[2] * x[2] + x[3] * x[3]); }
;                 ss = xadd<16>(ss); ss = xadd<32>(ss);
;                 const float rs = sect < 2 ? __builtin_amdgcn_rsqf(ss * (1.0f / 64.0f) + 1e-6f) * sc : 1.0f;
;                 bf16_t* rowp = base + ((unsigned)row * 1024u + (unsigned)colb);
; #pragma unroll
;                 for (int bj = 0; bj < 2; ++bj) {
;                     f32x4 v0 = v[bj][0] * rs, v1 = v[bj][1] * rs;
;                     if (sect < 2) { v0 = v0 * *(const f32x4*)(gp + 32 * bj); v1 = v1 * *(const f32x4*)(gp + 32 * bj + 4); }
;                     u32x4 w; w.x = cvt_pk_bf16(v0[0], v0[1]); w.y = cvt_pk_bf16(v0[2], v0[3]); w.z = cvt_pk_bf16(v1[0], v1[1]); w.w = cvt_pk_bf16(v1[2], v1[3]);
;                     *(u32x4*)(rowp + 32 * bj) = w; }
	v_add_f32_e32 v153, v153, v154
	v_mov_b32_e32 v154, v153
	s_nop 1
	v_permlane32_swap_b32_e32 v153, v154
	v_add_f32_e32 v153, v153, v154
	v_fmamk_f32 v153, v153, 0x3c800000, v222
	v_rsq_f32_e32 v153, v153
	s_nop 0
	v_mul_f32_e32 v153, s34, v153
	v_cndmask_b32_e32 v152, 1.0, v153, vcc
	v_mov_b64_e32 v[156:157], v[150:151]
	v_pk_mul_f32 v[128:129], v[128:129], v[152:153] op_sel_hi:[1,0]
	v_pk_mul_f32 v[130:131], v[130:131], v[152:153] op_sel_hi:[1,0]
	v_pk_mul_f32 v[128:129], v[128:129], v[200:201]
	v_pk_mul_f32 v[130:131], v[130:131], v[202:203]
	v_pk_mul_f32 v[132:133], v[132:133], v[152:153] op_sel_hi:[1,0]
	v_pk_mul_f32 v[134:135], v[134:135], v[152:153] op_sel_hi:[1,0]
	v_pk_mul_f32 v[132:133], v[132:133], v[204:205]
	v_pk_mul_f32 v[134:135], v[134:135], v[206:207]
	v_cvt_pk_bf16_f32 v128, v128, v129
	v_cvt_pk_bf16_f32 v129, v130, v131
	v_cvt_pk_bf16_f32 v130, v132, v133
	v_cvt_pk_bf16_f32 v131, v134, v135
	global_store_dwordx4 v[156:157], v[128:131], off
	v_pk_mul_f32 v[136:137], v[136:137], v[152:153] op_sel_hi:[1,0]
	v_pk_mul_f32 v[138:139], v[138:139], v[152:153] op_sel_hi:[1,0]
	v_pk_mul_f32 v[136:137], v[136:137], v[208:209]
	v_pk_mul_f32 v[138:139], v[138:139], v[210:211]
	v_pk_mul_f32 v[140:141], v[140:141], v[152:153] op_sel_hi:[1,0]
	v_pk_mul_f32 v[142:143], v[142:143], v[152:153] op_sel_hi:[1,0]
	v_pk_mul_f32 v[140:141], v[140:141], v[212:213]
	v_pk_mul_f32 v[142:143], v[142:143], v[214:215]
	v_cvt_pk_bf16_f32 v136, v136, v137
	v_cvt_pk_bf16_f32 v137, v138, v139
	v_cvt_pk_bf16_f32 v138, v140, v141
	v_cvt_pk_bf16_f32 v139, v142, v143
	global_store_dwordx4 v[156:157], v[136:139], off offset:64
	v_fmamk_f32 v152, v173, 0x3a800000, v222
	v_rsq_f32_e32 v152, v152
	s_nop 0
	v_pk_fma_f32 v[128:129], v[108:109], v[152:153], v[184:185] op_sel_hi:[1,0,1]
	v_pk_fma_f32 v[130:131], v[110:111], v[152:153], v[186:187] op_sel_hi:[1,0,1]
	v_pk_fma_f32 v[132:133], v[104:105], v[152:153], v[188:189] op_sel_hi:[1,0,1]
	v_pk_fma_f32 v[134:135], v[106:107], v[152:153], v[190:191] op_sel_hi:[1,0,1]
	v_pk_fma_f32 v[136:137], v[100:101], v[152:153], v[192:193] op_sel_hi:[1,0,1]
	v_pk_fma_f32 v[138:139], v[102:103], v[152:153], v[194:195] op_sel_hi:[1,0,1]
	v_pk_fma_f32 v[140:141], v[96:97], v[152:153], v[196:197] op_sel_hi:[1,0,1]
	v_pk_fma_f32 v[142:143], v[98:99], v[152:153], v[198:199] op_sel_hi:[1,0,1]
	v_mul_f32_e32 v154, v129, v129
	v_mul_f32_e32 v155, v131, v131
	v_fmac_f32_e32 v154, v128, v128
	v_fmac_f32_e32 v155, v130, v130
	v_add_f32_e32 v154, v154, v155
	v_add_f32_e32 v153, 0, v154
	v_mul_f32_e32 v154, v133, v133
	v_mul_f32_e32 v155, v135, v135
	v_fmac_f32_e32 v154, v132, v132
	v_fmac_f32_e32 v155, v134, v134
	v_add_f32_e32 v154, v154, v155
	v_add_f32_e32 v153, v153, v154
	v_mul_f32_e32 v154, v137, v137
	v_mul_f32_e32 v155, v139, v139
	v_fmac_f32_e32 v154, v136, v136
	v_fmac_f32_e32 v155, v138, v138
	v_add_f32_e32 v154, v154, v155
	v_add_f32_e32 v153, v153, v154
	v_mul_f32_e32 v154, v141, v141
	v_mul_f32_e32 v155, v143, v143
	v_fmac_f32_e32 v154, v140, v140
	v_fmac_f32_e32 v155, v142, v142
	v_add_f32_e32 v154, v154, v155
	v_add_f32_e32 v153, v153, v154
	ds_swizzle_b32 v154, v153 offset:swizzle(SWAP,16)
	s_waitcnt lgkmcnt(0)
	v_add_f32_e32 v153, v153, v154
	v_mov_b32_e32 v154, v153
	s_nop 1
	v_permlane32_swap_b32_e32 v153, v154
	v_add_f32_e32 v153, v153, v154
	v_fmamk_f32 v153, v153, 0x3c800000, v222
	v_rsq_f32_e32 v153, v153
	s_nop 0
	v_mul_f32_e32 v153, s34, v153
	v_cndmask_b32_e32 v152, 1.0, v153, vcc
	s_mov_b32 s2, 0x8000
	s_mov_b32 s3, 0
	v_lshl_add_u64 v[156:157], v[150:151], 0, s[2:3]
	v_pk_mul_f32 v[128:129], v[128:129], v[152:153] op_sel_hi:[1,0]
	v_pk_mul_f32 v[130:131], v[130:131], v[152:153] op_sel_hi:[1,0]
	v_pk_mul_f32 v[128:129], v[128:129], v[200:201]
	v_pk_mul_f32 v[130:131], v[130:131], v[202:203]
	v_pk_mul_f32 v[132:133], v[132:133], v[152:153] op_sel_hi:[1,0]
	v_pk_mul_f32 v[134:135], v[134:135], v[152:153] op_sel_hi:[1,0]
	v_pk_mul_f32 v[132:133], v[132:133], v[204:205]
	v_pk_mul_f32 v[134:135], v[134:135], v[206:207]
	v_cvt_pk_bf16_f32 v128, v128, v129
	v_cvt_pk_bf16_f32 v129, v130, v131
	v_cvt_pk_bf16_f32 v130, v132, v133
	v_cvt_pk_bf16_f32 v131, v134, v135
	global_store_dwordx4 v[156:157], v[128:131], off
	v_pk_mul_f32 v[136:137], v[136:137], v[152:153] op_sel_hi:[1,0]
	v_pk_mul_f32 v[138:139], v[138:139], v[152:153] op_sel_hi:[1,0]
	v_pk_mul_f32 v[136:137], v[136:137], v[208:209]
	v_pk_mul_f32 v[138:139], v[138:139], v[210:211]
	v_pk_mul_f32 v[140:141], v[140:141], v[152:153] op_sel_hi:[1,0]
	v_pk_mul_f32 v[142:143], v[142:143], v[152:153] op_sel_hi:[1,0]
	v_pk_mul_f32 v[140:141], v[140:141], v[212:213]
	v_pk_mul_f32 v[142:143], v[142:143], v[214:215]
	v_cvt_pk_bf16_f32 v136, v136, v137
	v_cvt_pk_bf16_f32 v137, v138, v139
	v_cvt_pk_bf16_f32 v138, v140, v141
	v_cvt_pk_bf16_f32 v139, v142, v143
	global_store_dwordx4 v[156:157], v[136:139], off offset:64
	v_fmamk_f32 v152, v174, 0x3a800000, v222
	v_rsq_f32_e32 v152, v152
	s_nop 0
	v_pk_fma_f32 v[128:129], v[92:93], v[152:153], v[184:185] op_sel_hi:[1,0,1]
	v_pk_fma_f32 v[130:131], v[94:95], v[152:153], v[186:187] op_sel_hi:[1,0,1]
	v_pk_fma_f32 v[132:133], v[88:89], v[152:153], v[188:189] op_sel_hi:[1,0,1]
	v_pk_fma_f32 v[134:135], v[90:91], v[152:153], v[190:191] op_sel_hi:[1,0,1]
	v_pk_fma_f32 v[136:137], v[84:85], v[152:153], v[192:193] op_sel_hi:[1,0,1]
	v_pk_fma_f32 v[138:139], v[86:87], v[152:153], v[194:195] op_sel_hi:[1,0,1]
	v_pk_fma_f32 v[140:141], v[80:81], v[152:153], v[196:197] op_sel_hi:[1,0,1]
	v_pk_fma_f32 v[142:143], v[82:83], v[152:153], v[198:199] op_sel_hi:[1,0,1]
	v_mul_f32_e32 v154, v129, v129
	v_mul_f32_e32 v155, v131, v131
	v_fmac_f32_e32 v154, v128, v128
	v_fmac_f32_e32 v155, v130, v130
	v_add_f32_e32 v154, v154, v155
	v_add_f32_e32 v153, 0, v154
	v_mul_f32_e32 v154, v133, v133
	v_mul_f32_e32 v155, v135, v135
	v_fmac_f32_e32 v154, v132, v132
	v_fmac_f32_e32 v155, v134, v134
	v_add_f32_e32 v154, v154, v155
	v_add_f32_e32 v153, v153, v154
	v_mul_f32_e32 v154, v137, v137
	v_mul_f32_e32 v155, v139, v139
	v_fmac_f32_e32 v154, v136, v136
	v_fmac_f32_e32 v155, v138, v138
	v_add_f32_e32 v154, v154, v155
	v_add_f32_e32 v153, v153, v154
	v_mul_f32_e32 v154, v141, v141
	v_mul_f32_e32 v155, v143, v143
	v_fmac_f32_e32 v154, v140, v140
	v_fmac_f32_e32 v155, v142, v142
	v_add_f32_e32 v154, v154, v155
	v_add_f32_e32 v153, v153, v154
	ds_swizzle_b32 v154, v153 offset:swizzle(SWAP,16)
	s_waitcnt lgkmcnt(0)
; __device__ __forceinline__ unsigned cvt_pk_bf16(float lo, float hi) { unsigned r; asm volatile("v_cvt_pk_bf16_f32 %0, %1, %2" : "=v"(r) : "v"(lo), "v"(hi)); return r; }
;     static __device__ __forceinline__ void run(const f32x4 (&acc)[2][2][4][2], const Unit& u, int wr, int wc, int fr, int fq, bf16_t* Q, bf16_t* K, bf16_t* V, const float* qg, const float* kg, float qscale, const float* ssqA, const float* bvec) {
;     ...
;                 const int row = row0 + ai * HALF + m * 16; const float r = row_scale(ssqA, nullptr, row);
;                 f32x4 v[2][2]; float ss = 0.f;
; #pragma unroll
;                 for (int bj = 0; bj < 2; ++bj)
; #pragma unroll
;                     for (int n = 0; n < 2; ++n) { const f32x4 x = acc[ai][bj][m][n] * r + *(const f32x4*)(bp + bj * HALF + 4 * n); v[bj][n] = x; ss += (x[0] * x[0] + x[1] * x[1]) + (x[2] * x[2] + x[3] * x[3]); }
;                 ss = xadd<16>(ss); ss = xadd<32>(ss);
;                 const float rs = sect < 2 ? __builtin_amdgcn_rsqf(ss * (1.0f / 64.0f) + 1e-6f) * sc : 1.0f;
;                 bf16_t* rowp = base + ((unsigned)row * 1024u + (unsigned)colb);
; #pragma unroll
;                 for (int bj = 0; bj < 2; ++bj) {
;                     f32x4 v0 = v[bj][0] * rs, v1 = v[bj][1] * rs;
;                     if (sect < 2) { v0 = v0 * *(const f32x4*)(gp + 32 * bj); v1 = v1 * *(const f32x4*)(gp + 32 * bj + 4); }
;                     u32x4 w; w.x = cvt_pk_bf16(v0[0], v0[1]); w.y = cvt_pk_bf16(v0[2], v0[3]); w.z = cvt_pk_bf16(v1[0], v1[1]); w.w = cvt_pk_bf16(v1[2], v1[3]);
;                     *(u32x4*)(rowp + 32 * bj) = w; }
	v_add_f32_e32 v153, v153, v154
	v_mov_b32_e32 v154, v153
	s_nop 1
	v_permlane32_swap_b32_e32 v153, v154
	v_add_f32_e32 v153, v153, v154
	v_fmamk_f32 v153, v153, 0x3c800000, v222
	v_rsq_f32_e32 v153, v153
	s_nop 0
	v_mul_f32_e32 v153, s34, v153
	v_cndmask_b32_e32 v152, 1.0, v153, vcc
	s_mov_b32 s2, 0x10000
	s_mov_b32 s3, 0
	v_lshl_add_u64 v[156:157], v[150:151], 0, s[2:3]
	v_pk_mul_f32 v[128:129], v[128:129], v[152:153] op_sel_hi:[1,0]
	v_pk_mul_f32 v[130:131], v[130:131], v[152:153] op_sel_hi:[1,0]
	v_pk_mul_f32 v[128:129], v[128:129], v[200:201]
	v_pk_mul_f32 v[130:131], v[130:131], v[202:203]
	v_pk_mul_f32 v[132:133], v[132:133], v[152:153] op_sel_hi:[1,0]
	v_pk_mul_f32 v[134:135], v[134:135], v[152:153] op_sel_hi:[1,0]
	v_pk_mul_f32 v[132:133], v[132:133], v[204:205]
	v_pk_mul_f32 v[134:135], v[134:135], v[206:207]
	v_cvt_pk_bf16_f32 v128, v128, v129
	v_cvt_pk_bf16_f32 v129, v130, v131
	v_cvt_pk_bf16_f32 v130, v132, v133
	v_cvt_pk_bf16_f32 v131, v134, v135
	global_store_dwordx4 v[156:157], v[128:131], off
	v_pk_mul_f32 v[136:137], v[136:137], v[152:153] op_sel_hi:[1,0]
	v_pk_mul_f32 v[138:139], v[138:139], v[152:153] op_sel_hi:[1,0]
	v_pk_mul_f32 v[136:137], v[136:137], v[208:209]
	v_pk_mul_f32 v[138:139], v[138:139], v[210:211]
	v_pk_mul_f32 v[140:141], v[140:141], v[152:153] op_sel_hi:[1,0]
	v_pk_mul_f32 v[142:143], v[142:143], v[152:153] op_sel_hi:[1,0]
	v_pk_mul_f32 v[140:141], v[140:141], v[212:213]
	v_pk_mul_f32 v[142:143], v[142:143], v[214:215]
	v_cvt_pk_bf16_f32 v136, v136, v137
	v_cvt_pk_bf16_f32 v137, v138, v139
	v_cvt_pk_bf16_f32 v138, v140, v141
	v_cvt_pk_bf16_f32 v139, v142, v143
	global_store_dwordx4 v[156:157], v[136:139], off offset:64
	v_fmamk_f32 v152, v175, 0x3a800000, v222
	v_rsq_f32_e32 v152, v152
	s_nop 0
	v_pk_fma_f32 v[128:129], v[76:77], v[152:153], v[184:185] op_sel_hi:[1,0,1]
	v_pk_fma_f32 v[130:131], v[78:79], v[152:153], v[186:187] op_sel_hi:[1,0,1]
	v_pk_fma_f32 v[132:133], v[72:73], v[152:153], v[188:189] op_sel_hi:[1,0,1]
	v_pk_fma_f32 v[134:135], v[74:75], v[152:153], v[190:191] op_sel_hi:[1,0,1]
	v_pk_fma_f32 v[136:137], v[68:69], v[152:153], v[192:193] op_sel_hi:[1,0,1]
	v_pk_fma_f32 v[138:139], v[70:71], v[152:153], v[194:195] op_sel_hi:[1,0,1]
	v_pk_fma_f32 v[140:141], v[64:65], v[152:153], v[196:197] op_sel_hi:[1,0,1]
	v_pk_fma_f32 v[142:143], v[66:67], v[152:153], v[198:199] op_sel_hi:[1,0,1]
	v_mul_f32_e32 v154, v129, v129
	v_mul_f32_e32 v155, v131, v131
	v_fmac_f32_e32 v154, v128, v128
	v_fmac_f32_e32 v155, v130, v130
	v_add_f32_e32 v154, v154, v155
	v_add_f32_e32 v153, 0, v154
	v_mul_f32_e32 v154, v133, v133
	v_mul_f32_e32 v155, v135, v135
	v_fmac_f32_e32 v154, v132, v132
	v_fmac_f32_e32 v155, v134, v134
	v_add_f32_e32 v154, v154, v155
	v_add_f32_e32 v153, v153, v154
	v_mul_f32_e32 v154, v137, v137
	v_mul_f32_e32 v155, v139, v139
	v_fmac_f32_e32 v154, v136, v136
	v_fmac_f32_e32 v155, v138, v138
	v_add_f32_e32 v154, v154, v155
	v_add_f32_e32 v153, v153, v154
	v_mul_f32_e32 v154, v141, v141
	v_mul_f32_e32 v155, v143, v143
	v_fmac_f32_e32 v154, v140, v140
	v_fmac_f32_e32 v155, v142, v142
	v_add_f32_e32 v154, v154, v155
	v_add_f32_e32 v153, v153, v154
	ds_swizzle_b32 v154, v153 offset:swizzle(SWAP,16)
	s_waitcnt lgkmcnt(0)
	v_add_f32_e32 v153, v153, v154
	v_mov_b32_e32 v154, v153
	s_nop 1
	v_permlane32_swap_b32_e32 v153, v154
	v_add_f32_e32 v153, v153, v154
	v_fmamk_f32 v153, v153, 0x3c800000, v222
	v_rsq_f32_e32 v153, v153
	s_nop 0
	v_mul_f32_e32 v153, s34, v153
	v_cndmask_b32_e32 v152, 1.0, v153, vcc
	s_mov_b32 s2, 0x18000
	s_mov_b32 s3, 0
	v_lshl_add_u64 v[156:157], v[150:151], 0, s[2:3]
	v_pk_mul_f32 v[128:129], v[128:129], v[152:153] op_sel_hi:[1,0]
	v_pk_mul_f32 v[130:131], v[130:131], v[152:153] op_sel_hi:[1,0]
	v_pk_mul_f32 v[128:129], v[128:129], v[200:201]
	v_pk_mul_f32 v[130:131], v[130:131], v[202:203]
	v_pk_mul_f32 v[132:133], v[132:133], v[152:153] op_sel_hi:[1,0]
	v_pk_mul_f32 v[134:135], v[134:135], v[152:153] op_sel_hi:[1,0]
	v_pk_mul_f32 v[132:133], v[132:133], v[204:205]
	v_pk_mul_f32 v[134:135], v[134:135], v[206:207]
	v_cvt_pk_bf16_f32 v128, v128, v129
	v_cvt_pk_bf16_f32 v129, v130, v131
	v_cvt_pk_bf16_f32 v130, v132, v133
	v_cvt_pk_bf16_f32 v131, v134, v135
	global_store_dwordx4 v[156:157], v[128:131], off
	v_pk_mul_f32 v[136:137], v[136:137], v[152:153] op_sel_hi:[1,0]
	v_pk_mul_f32 v[138:139], v[138:139], v[152:153] op_sel_hi:[1,0]
	v_pk_mul_f32 v[136:137], v[136:137], v[208:209]
	v_pk_mul_f32 v[138:139], v[138:139], v[210:211]
	v_pk_mul_f32 v[140:141], v[140:141], v[152:153] op_sel_hi:[1,0]
	v_pk_mul_f32 v[142:143], v[142:143], v[152:153] op_sel_hi:[1,0]
	v_pk_mul_f32 v[140:141], v[140:141], v[212:213]
	v_pk_mul_f32 v[142:143], v[142:143], v[214:215]
	v_cvt_pk_bf16_f32 v136, v136, v137
	v_cvt_pk_bf16_f32 v137, v138, v139
	v_cvt_pk_bf16_f32 v138, v140, v141
	v_cvt_pk_bf16_f32 v139, v142, v143
	global_store_dwordx4 v[156:157], v[136:139], off offset:64
	v_fmamk_f32 v152, v180, 0x3a800000, v222
	v_rsq_f32_e32 v152, v152
	s_nop 0
	v_pk_fma_f32 v[128:129], v[60:61], v[152:153], v[184:185] op_sel_hi:[1,0,1]
	v_pk_fma_f32 v[130:131], v[62:63], v[152:153], v[186:187] op_sel_hi:[1,0,1]
	v_pk_fma_f32 v[132:133], v[56:57], v[152:153], v[188:189] op_sel_hi:[1,0,1]
	v_pk_fma_f32 v[134:135], v[58:59], v[152:153], v[190:191] op_sel_hi:[1,0,1]
	v_pk_fma_f32 v[136:137], v[52:53], v[152:153], v[192:193] op_sel_hi:[1,0,1]
	v_pk_fma_f32 v[138:139], v[54:55], v[152:153], v[194:195] op_sel_hi:[1,0,1]
	v_pk_fma_f32 v[140:141], v[48:49], v[152:153], v[196:197] op_sel_hi:[1,0,1]
	v_pk_fma_f32 v[142:143], v[50:51], v[152:153], v[198:199] op_sel_hi:[1,0,1]
	v_mul_f32_e32 v154, v129, v129
	v_mul_f32_e32 v155, v131, v131
	v_fmac_f32_e32 v154, v128, v128
	v_fmac_f32_e32 v155, v130, v130
	v_add_f32_e32 v154, v154, v155
	v_add_f32_e32 v153, 0, v154
	v_mul_f32_e32 v154, v133, v133
	v_mul_f32_e32 v155, v135, v135
	v_fmac_f32_e32 v154, v132, v132
	v_fmac_f32_e32 v155, v134, v134
	v_add_f32_e32 v154, v154, v155
	v_add_f32_e32 v153, v153, v154
	v_mul_f32_e32 v154, v137, v137
	v_mul_f32_e32 v155, v139, v139
	v_fmac_f32_e32 v154, v136, v136
	v_fmac_f32_e32 v155, v138, v138
	v_add_f32_e32 v154, v154, v155
	v_add_f32_e32 v153, v153, v154
	v_mul_f32_e32 v154, v141, v141
	v_mul_f32_e32 v155, v143, v143
	v_fmac_f32_e32 v154, v140, v140
	v_fmac_f32_e32 v155, v142, v142
	v_add_f32_e32 v154, v154, v155
	v_add_f32_e32 v153, v153, v154
	ds_swizzle_b32 v154, v153 offset:swizzle(SWAP,16)
	s_waitcnt lgkmcnt(0)
; __device__ __forceinline__ unsigned cvt_pk_bf16(float lo, float hi) { unsigned r; asm volatile("v_cvt_pk_bf16_f32 %0, %1, %2" : "=v"(r) : "v"(lo), "v"(hi)); return r; }
;     static __device__ __forceinline__ void run(const f32x4 (&acc)[2][2][4][2], const Unit& u, int wr, int wc, int fr, int fq, bf16_t* Q, bf16_t* K, bf16_t* V, const float* qg, const float* kg, float qscale, const float* ssqA, const float* bvec) {
;     ...
;                 const int row = row0 + ai * HALF + m * 16; const float r = row_scale(ssqA, nullptr, row);
;                 f32x4 v[2][2]; float ss = 0.f;
; #pragma unroll
;                 for (int bj = 0; bj < 2; ++bj)
; #pragma unroll
;                     for (int n = 0; n < 2; ++n) { const f32x4 x = acc[ai][bj][m][n] * r + *(const f32x4*)(bp + bj * HALF + 4 * n); v[bj][n] = x; ss += (x[0] * x[0] + x[1] * x[1]) + (x[2] * x[2] + x[3] * x[3]); }
;                 ss = xadd<16>(ss); ss = xadd<32>(ss);
;                 const float rs = sect < 2 ? __builtin_amdgcn_rsqf(ss * (1.0f / 64.0f) + 1e-6f) * sc : 1.0f;
;                 bf16_t* rowp = base + ((unsigned)row * 1024u + (unsigned)colb);
; #pragma unroll
;                 for (int bj = 0; bj < 2; ++bj) {
;                     f32x4 v0 = v[bj][0] * rs, v1 = v[bj][1] * rs;
;                     if (sect < 2) { v0 = v0 * *(const f32x4*)(gp + 32 * bj); v1 = v1 * *(const f32x4*)(gp + 32 * bj + 4); }
;                     u32x4 w; w.x = cvt_pk_bf16(v0[0], v0[1]); w.y = cvt_pk_bf16(v0[2], v0[3]); w.z = cvt_pk_bf16(v1[0], v1[1]); w.w = cvt_pk_bf16(v1[2], v1[3]);
;                     *(u32x4*)(rowp + 32 * bj) = w; }
	v_add_f32_e32 v153, v153, v154
	v_mov_b32_e32 v154, v153
	s_nop 1
	v_permlane32_swap_b32_e32 v153, v154
	v_add_f32_e32 v153, v153, v154
	v_fmamk_f32 v153, v153, 0x3c800000, v222
	v_rsq_f32_e32 v153, v153
	s_nop 0
	v_mul_f32_e32 v153, s34, v153
	v_cndmask_b32_e32 v152, 1.0, v153, vcc
	s_mov_b32 s2, 0x40000
	s_mov_b32 s3, 0
	v_lshl_add_u64 v[156:157], v[150:151], 0, s[2:3]
	v_pk_mul_f32 v[128:129], v[128:129], v[152:153] op_sel_hi:[1,0]
	v_pk_mul_f32 v[130:131], v[130:131], v[152:153] op_sel_hi:[1,0]
	v_pk_mul_f32 v[128:129], v[128:129], v[200:201]
	v_pk_mul_f32 v[130:131], v[130:131], v[202:203]
	v_pk_mul_f32 v[132:133], v[132:133], v[152:153] op_sel_hi:[1,0]
	v_pk_mul_f32 v[134:135], v[134:135], v[152:153] op_sel_hi:[1,0]
	v_pk_mul_f32 v[132:133], v[132:133], v[204:205]
	v_pk_mul_f32 v[134:135], v[134:135], v[206:207]
	v_cvt_pk_bf16_f32 v128, v128, v129
	v_cvt_pk_bf16_f32 v129, v130, v131
	v_cvt_pk_bf16_f32 v130, v132, v133
	v_cvt_pk_bf16_f32 v131, v134, v135
	global_store_dwordx4 v[156:157], v[128:131], off
	v_pk_mul_f32 v[136:137], v[136:137], v[152:153] op_sel_hi:[1,0]
	v_pk_mul_f32 v[138:139], v[138:139], v[152:153] op_sel_hi:[1,0]
	v_pk_mul_f32 v[136:137], v[136:137], v[208:209]
	v_pk_mul_f32 v[138:139], v[138:139], v[210:211]
	v_pk_mul_f32 v[140:141], v[140:141], v[152:153] op_sel_hi:[1,0]
	v_pk_mul_f32 v[142:143], v[142:143], v[152:153] op_sel_hi:[1,0]
	v_pk_mul_f32 v[140:141], v[140:141], v[212:213]
	v_pk_mul_f32 v[142:143], v[142:143], v[214:215]
	v_cvt_pk_bf16_f32 v136, v136, v137
	v_cvt_pk_bf16_f32 v137, v138, v139
	v_cvt_pk_bf16_f32 v138, v140, v141
	v_cvt_pk_bf16_f32 v139, v142, v143
	global_store_dwordx4 v[156:157], v[136:139], off offset:64
	v_fmamk_f32 v152, v181, 0x3a800000, v222
	v_rsq_f32_e32 v152, v152
	s_nop 0
	v_pk_fma_f32 v[128:129], v[44:45], v[152:153], v[184:185] op_sel_hi:[1,0,1]
	v_pk_fma_f32 v[130:131], v[46:47], v[152:153], v[186:187] op_sel_hi:[1,0,1]
	v_pk_fma_f32 v[132:133], v[40:41], v[152:153], v[188:189] op_sel_hi:[1,0,1]
	v_pk_fma_f32 v[134:135], v[42:43], v[152:153], v[190:191] op_sel_hi:[1,0,1]
	v_pk_fma_f32 v[136:137], v[36:37], v[152:153], v[192:193] op_sel_hi:[1,0,1]
	v_pk_fma_f32 v[138:139], v[38:39], v[152:153], v[194:195] op_sel_hi:[1,0,1]
	v_pk_fma_f32 v[140:141], v[32:33], v[152:153], v[196:197] op_sel_hi:[1,0,1]
	v_pk_fma_f32 v[142:143], v[34:35], v[152:153], v[198:199] op_sel_hi:[1,0,1]
	v_mul_f32_e32 v154, v129, v129
	v_mul_f32_e32 v155, v131, v131
	v_fmac_f32_e32 v154, v128, v128
	v_fmac_f32_e32 v155, v130, v130
	v_add_f32_e32 v154, v154, v155
	v_add_f32_e32 v153, 0, v154
	v_mul_f32_e32 v154, v133, v133
	v_mul_f32_e32 v155, v135, v135
	v_fmac_f32_e32 v154, v132, v132
	v_fmac_f32_e32 v155, v134, v134
	v_add_f32_e32 v154, v154, v155
	v_add_f32_e32 v153, v153, v154
	v_mul_f32_e32 v154, v137, v137
	v_mul_f32_e32 v155, v139, v139
	v_fmac_f32_e32 v154, v136, v136
	v_fmac_f32_e32 v155, v138, v138
	v_add_f32_e32 v154, v154, v155
	v_add_f32_e32 v153, v153, v154
	v_mul_f32_e32 v154, v141, v141
	v_mul_f32_e32 v155, v143, v143
	v_fmac_f32_e32 v154, v140, v140
	v_fmac_f32_e32 v155, v142, v142
	v_add_f32_e32 v154, v154, v155
	v_add_f32_e32 v153, v153, v154
	ds_swizzle_b32 v154, v153 offset:swizzle(SWAP,16)
	s_waitcnt lgkmcnt(0)
	v_add_f32_e32 v153, v153, v154
	v_mov_b32_e32 v154, v153
	s_nop 1
	v_permlane32_swap_b32_e32 v153, v154
	v_add_f32_e32 v153, v153, v154
	v_fmamk_f32 v153, v153, 0x3c800000, v222
	v_rsq_f32_e32 v153, v153
	s_nop 0
	v_mul_f32_e32 v153, s34, v153
	v_cndmask_b32_e32 v152, 1.0, v153, vcc
	s_mov_b32 s2, 0x48000
	s_mov_b32 s3, 0
	v_lshl_add_u64 v[156:157], v[150:151], 0, s[2:3]
	v_pk_mul_f32 v[128:129], v[128:129], v[152:153] op_sel_hi:[1,0]
	v_pk_mul_f32 v[130:131], v[130:131], v[152:153] op_sel_hi:[1,0]
	v_pk_mul_f32 v[128:129], v[128:129], v[200:201]
	v_pk_mul_f32 v[130:131], v[130:131], v[202:203]
	v_pk_mul_f32 v[132:133], v[132:133], v[152:153] op_sel_hi:[1,0]
	v_pk_mul_f32 v[134:135], v[134:135], v[152:153] op_sel_hi:[1,0]
	v_pk_mul_f32 v[132:133], v[132:133], v[204:205]
	v_pk_mul_f32 v[134:135], v[134:135], v[206:207]
	v_cvt_pk_bf16_f32 v128, v128, v129
	v_cvt_pk_bf16_f32 v129, v130, v131
	v_cvt_pk_bf16_f32 v130, v132, v133
	v_cvt_pk_bf16_f32 v131, v134, v135
	global_store_dwordx4 v[156:157], v[128:131], off
	v_pk_mul_f32 v[136:137], v[136:137], v[152:153] op_sel_hi:[1,0]
	v_pk_mul_f32 v[138:139], v[138:139], v[152:153] op_sel_hi:[1,0]
	v_pk_mul_f32 v[136:137], v[136:137], v[208:209]
	v_pk_mul_f32 v[138:139], v[138:139], v[210:211]
	v_pk_mul_f32 v[140:141], v[140:141], v[152:153] op_sel_hi:[1,0]
	v_pk_mul_f32 v[142:143], v[142:143], v[152:153] op_sel_hi:[1,0]
	v_pk_mul_f32 v[140:141], v[140:141], v[212:213]
	v_pk_mul_f32 v[142:143], v[142:143], v[214:215]
	v_cvt_pk_bf16_f32 v136, v136, v137
	v_cvt_pk_bf16_f32 v137, v138, v139
	v_cvt_pk_bf16_f32 v138, v140, v141
	v_cvt_pk_bf16_f32 v139, v142, v143
	global_store_dwordx4 v[156:157], v[136:139], off offset:64
	v_fmamk_f32 v152, v182, 0x3a800000, v222
	v_rsq_f32_e32 v152, v152
	s_nop 0
	v_pk_fma_f32 v[128:129], v[28:29], v[152:153], v[184:185] op_sel_hi:[1,0,1]
	v_pk_fma_f32 v[130:131], v[30:31], v[152:153], v[186:187] op_sel_hi:[1,0,1]
	v_pk_fma_f32 v[132:133], v[24:25], v[152:153], v[188:189] op_sel_hi:[1,0,1]
	v_pk_fma_f32 v[134:135], v[26:27], v[152:153], v[190:191] op_sel_hi:[1,0,1]
	v_pk_fma_f32 v[136:137], v[20:21], v[152:153], v[192:193] op_sel_hi:[1,0,1]
	v_pk_fma_f32 v[138:139], v[22:23], v[152:153], v[194:195] op_sel_hi:[1,0,1]
	v_pk_fma_f32 v[140:141], v[16:17], v[152:153], v[196:197] op_sel_hi:[1,0,1]
	v_pk_fma_f32 v[142:143], v[18:19], v[152:153], v[198:199] op_sel_hi:[1,0,1]
	v_mul_f32_e32 v154, v129, v129
	v_mul_f32_e32 v155, v131, v131
	v_fmac_f32_e32 v154, v128, v128
	v_fmac_f32_e32 v155, v130, v130
	v_add_f32_e32 v154, v154, v155
	v_add_f32_e32 v153, 0, v154
	v_mul_f32_e32 v154, v133, v133
	v_mul_f32_e32 v155, v135, v135
	v_fmac_f32_e32 v154, v132, v132
	v_fmac_f32_e32 v155, v134, v134
	v_add_f32_e32 v154, v154, v155
	v_add_f32_e32 v153, v153, v154
	v_mul_f32_e32 v154, v137, v137
	v_mul_f32_e32 v155, v139, v139
	v_fmac_f32_e32 v154, v136, v136
	v_fmac_f32_e32 v155, v138, v138
	v_add_f32_e32 v154, v154, v155
	v_add_f32_e32 v153, v153, v154
	v_mul_f32_e32 v154, v141, v141
	v_mul_f32_e32 v155, v143, v143
	v_fmac_f32_e32 v154, v140, v140
	v_fmac_f32_e32 v155, v142, v142
	v_add_f32_e32 v154, v154, v155
	v_add_f32_e32 v153, v153, v154
	ds_swizzle_b32 v154, v153 offset:swizzle(SWAP,16)
	s_waitcnt lgkmcnt(0)
; __device__ __forceinline__ unsigned cvt_pk_bf16(float lo, float hi) { unsigned r; asm volatile("v_cvt_pk_bf16_f32 %0, %1, %2" : "=v"(r) : "v"(lo), "v"(hi)); return r; }
;     static __device__ __forceinline__ void run(const f32x4 (&acc)[2][2][4][2], const Unit& u, int wr, int wc, int fr, int fq, bf16_t* Q, bf16_t* K, bf16_t* V, const float* qg, const float* kg, float qscale, const float* ssqA, const float* bvec) {
;     ...
;                 const int row = row0 + ai * HALF + m * 16; const float r = row_scale(ssqA, nullptr, row);
;                 f32x4 v[2][2]; float ss = 0.f;
; #pragma unroll
;                 for (int bj = 0; bj < 2; ++bj)
; #pragma unroll
;                     for (int n = 0; n < 2; ++n) { const f32x4 x = acc[ai][bj][m][n] * r + *(const f32x4*)(bp + bj * HALF + 4 * n); v[bj][n] = x; ss += (x[0] * x[0] + x[1] * x[1]) + (x[2] * x[2] + x[3] * x[3]); }
;                 ss = xadd<16>(ss); ss = xadd<32>(ss);
;                 const float rs = sect < 2 ? __builtin_amdgcn_rsqf(ss * (1.0f / 64.0f) + 1e-6f) * sc : 1.0f;
;                 bf16_t* rowp = base + ((unsigned)row * 1024u + (unsigned)colb);
; #pragma unroll
;                 for (int bj = 0; bj < 2; ++bj) {
;                     f32x4 v0 = v[bj][0] * rs, v1 = v[bj][1] * rs;
;                     if (sect < 2) { v0 = v0 * *(const f32x4*)(gp + 32 * bj); v1 = v1 * *(const f32x4*)(gp + 32 * bj + 4); }
;                     u32x4 w; w.x = cvt_pk_bf16(v0[0], v0[1]); w.y = cvt_pk_bf16(v0[2], v0[3]); w.z = cvt_pk_bf16(v1[0], v1[1]); w.w = cvt_pk_bf16(v1[2], v1[3]);
;                     *(u32x4*)(rowp + 32 * bj) = w; }
	v_add_f32_e32 v153, v153, v154
	v_mov_b32_e32 v154, v153
	s_nop 1
	v_permlane32_swap_b32_e32 v153, v154
	v_add_f32_e32 v153, v153, v154
	v_fmamk_f32 v153, v153, 0x3c800000, v222
	v_rsq_f32_e32 v153, v153
	s_nop 0
	v_mul_f32_e32 v153, s34, v153
	v_cndmask_b32_e32 v152, 1.0, v153, vcc
	s_mov_b32 s2, 0x50000
	s_mov_b32 s3, 0
	v_lshl_add_u64 v[156:157], v[150:151], 0, s[2:3]
	v_pk_mul_f32 v[128:129], v[128:129], v[152:153] op_sel_hi:[1,0]
	v_pk_mul_f32 v[130:131], v[130:131], v[152:153] op_sel_hi:[1,0]
	v_pk_mul_f32 v[128:129], v[128:129], v[200:201]
	v_pk_mul_f32 v[130:131], v[130:131], v[202:203]
	v_pk_mul_f32 v[132:133], v[132:133], v[152:153] op_sel_hi:[1,0]
	v_pk_mul_f32 v[134:135], v[134:135], v[152:153] op_sel_hi:[1,0]
	v_pk_mul_f32 v[132:133], v[132:133], v[204:205]
	v_pk_mul_f32 v[134:135], v[134:135], v[206:207]
	v_cvt_pk_bf16_f32 v128, v128, v129
	v_cvt_pk_bf16_f32 v129, v130, v131
	v_cvt_pk_bf16_f32 v130, v132, v133
	v_cvt_pk_bf16_f32 v131, v134, v135
	global_store_dwordx4 v[156:157], v[128:131], off
	v_pk_mul_f32 v[136:137], v[136:137], v[152:153] op_sel_hi:[1,0]
	v_pk_mul_f32 v[138:139], v[138:139], v[152:153] op_sel_hi:[1,0]
	v_pk_mul_f32 v[136:137], v[136:137], v[208:209]
	v_pk_mul_f32 v[138:139], v[138:139], v[210:211]
	v_pk_mul_f32 v[140:141], v[140:141], v[152:153] op_sel_hi:[1,0]
	v_pk_mul_f32 v[142:143], v[142:143], v[152:153] op_sel_hi:[1,0]
	v_pk_mul_f32 v[140:141], v[140:141], v[212:213]
	v_pk_mul_f32 v[142:143], v[142:143], v[214:215]
	v_cvt_pk_bf16_f32 v136, v136, v137
	v_cvt_pk_bf16_f32 v137, v138, v139
	v_cvt_pk_bf16_f32 v138, v140, v141
	v_cvt_pk_bf16_f32 v139, v142, v143
	global_store_dwordx4 v[156:157], v[136:139], off offset:64
	v_fmamk_f32 v152, v183, 0x3a800000, v222
	v_rsq_f32_e32 v152, v152
	s_nop 0
	v_pk_fma_f32 v[128:129], v[12:13], v[152:153], v[184:185] op_sel_hi:[1,0,1]
	v_pk_fma_f32 v[130:131], v[14:15], v[152:153], v[186:187] op_sel_hi:[1,0,1]
	v_pk_fma_f32 v[132:133], v[8:9], v[152:153], v[188:189] op_sel_hi:[1,0,1]
	v_pk_fma_f32 v[134:135], v[10:11], v[152:153], v[190:191] op_sel_hi:[1,0,1]
	v_pk_fma_f32 v[136:137], v[4:5], v[152:153], v[192:193] op_sel_hi:[1,0,1]
	v_pk_fma_f32 v[138:139], v[6:7], v[152:153], v[194:195] op_sel_hi:[1,0,1]
	v_pk_fma_f32 v[140:141], v[0:1], v[152:153], v[196:197] op_sel_hi:[1,0,1]
	v_pk_fma_f32 v[142:143], v[2:3], v[152:153], v[198:199] op_sel_hi:[1,0,1]
	v_mul_f32_e32 v154, v129, v129
	v_mul_f32_e32 v155, v131, v131
	v_fmac_f32_e32 v154, v128, v128
	v_fmac_f32_e32 v155, v130, v130
	v_add_f32_e32 v154, v154, v155
	v_add_f32_e32 v153, 0, v154
	v_mul_f32_e32 v154, v133, v133
	v_mul_f32_e32 v155, v135, v135
	v_fmac_f32_e32 v154, v132, v132
	v_fmac_f32_e32 v155, v134, v134
	v_add_f32_e32 v154, v154, v155
	v_add_f32_e32 v153, v153, v154
	v_mul_f32_e32 v154, v137, v137
	v_mul_f32_e32 v155, v139, v139
	v_fmac_f32_e32 v154, v136, v136
	v_fmac_f32_e32 v155, v138, v138
	v_add_f32_e32 v154, v154, v155
	v_add_f32_e32 v153, v153, v154
	v_mul_f32_e32 v154, v141, v141
	v_mul_f32_e32 v155, v143, v143
	v_fmac_f32_e32 v154, v140, v140
	v_fmac_f32_e32 v155, v142, v142
	v_add_f32_e32 v154, v154, v155
	v_add_f32_e32 v153, v153, v154
	ds_swizzle_b32 v154, v153 offset:swizzle(SWAP,16)
	s_waitcnt lgkmcnt(0)
	v_add_f32_e32 v153, v153, v154
	v_mov_b32_e32 v154, v153
	s_nop 1
	v_permlane32_swap_b32_e32 v153, v154
	v_add_f32_e32 v153, v153, v154
	v_fmamk_f32 v153, v153, 0x3c800000, v222
	v_rsq_f32_e32 v153, v153
	s_nop 0
	v_mul_f32_e32 v153, s34, v153
	v_cndmask_b32_e32 v152, 1.0, v153, vcc
	s_mov_b32 s2, 0x58000
	s_mov_b32 s3, 0
	v_lshl_add_u64 v[156:157], v[150:151], 0, s[2:3]
	v_pk_mul_f32 v[128:129], v[128:129], v[152:153] op_sel_hi:[1,0]
	v_pk_mul_f32 v[130:131], v[130:131], v[152:153] op_sel_hi:[1,0]
	v_pk_mul_f32 v[128:129], v[128:129], v[200:201]
	v_pk_mul_f32 v[130:131], v[130:131], v[202:203]
	v_pk_mul_f32 v[132:133], v[132:133], v[152:153] op_sel_hi:[1,0]
	v_pk_mul_f32 v[134:135], v[134:135], v[152:153] op_sel_hi:[1,0]
	v_pk_mul_f32 v[132:133], v[132:133], v[204:205]
	v_pk_mul_f32 v[134:135], v[134:135], v[206:207]
	v_cvt_pk_bf16_f32 v128, v128, v129
	v_cvt_pk_bf16_f32 v129, v130, v131
	v_cvt_pk_bf16_f32 v130, v132, v133
	v_cvt_pk_bf16_f32 v131, v134, v135
	global_store_dwordx4 v[156:157], v[128:131], off
	v_pk_mul_f32 v[136:137], v[136:137], v[152:153] op_sel_hi:[1,0]
	v_pk_mul_f32 v[138:139], v[138:139], v[152:153] op_sel_hi:[1,0]
	v_pk_mul_f32 v[136:137], v[136:137], v[208:209]
	v_pk_mul_f32 v[138:139], v[138:139], v[210:211]
	v_pk_mul_f32 v[140:141], v[140:141], v[152:153] op_sel_hi:[1,0]
	v_pk_mul_f32 v[142:143], v[142:143], v[152:153] op_sel_hi:[1,0]
	v_pk_mul_f32 v[140:141], v[140:141], v[212:213]
	v_pk_mul_f32 v[142:143], v[142:143], v[214:215]
	v_cvt_pk_bf16_f32 v136, v136, v137
	v_cvt_pk_bf16_f32 v137, v138, v139
	v_cvt_pk_bf16_f32 v138, v140, v141
	v_cvt_pk_bf16_f32 v139, v142, v143
	global_store_dwordx4 v[156:157], v[136:139], off offset:64
	s_mov_b64 s[2:3], 0
